# P4 K-loop first iteration peeled as well (C=0 on first touch, both accumulator zero fills removed); P1/P3 as in the previous version
# speedup vs baseline: 1.0076x; 1.0017x over previous
; #define PG8_STAGE(bufoff, gbase, voff) do { _Pragma("unroll") for (int _i = 0; _i < 2; ++_i) \
;         __builtin_amdgcn_global_load_lds((const unsigned*)((const char*)(gbase) + (voff)[_i]), (PG8_LAS unsigned*)(lds + (bufoff) + ldsw + _i * 8192), 16, 0, 0); } while (0)
; #define PG8_WAIT_V(n) asm volatile("s_waitcnt vmcnt(" #n ")" ::: "memory")
; #define PG8_BAR __builtin_amdgcn_s_barrier()
; template <class Epi, class Sched, bool ALIGN_EPI = false, bool SP2 = false>
; __device__ __forceinline__ void gemm_phase(PG8_LAS unsigned char* lds, const Gemm g, const Sched& S, const Epi& E) {
;     ...
;     const char* cA = (const char*)g.A + (size_t)cur.pm * tstep; const char* cB = (const char*)g.Bt + (size_t)cur.pn * tstep;
;     S.a_ready(cur);
;     if constexpr (SP2) {
;         PG8_STAGE(PG8_SB(0, 0), cB, voffB); PG8_STAGE(PG8_SB(0, 1), cB + hstep, voffB); PG8_STAGE(PG8_SA(0, 0), cA, voffA); PG8_STAGE(PG8_SA(0, 1), cA + hstep, voffA);
;         if (wr == 1) PG8_BAR;
;         PG8_WAIT_V(2); PG8_BAR;
;         PG8_STAGE(PG8_SB(1, 0), cB + kstep, voffB); PG8_STAGE(PG8_SA(1, 0), cA + kstep, voffA); PG8_STAGE(PG8_SB(1, 1), cB + hstep + kstep, voffB);
;         PG8_WAIT_V(6); PG8_BAR;
;     } else {
;         PG8_STAGE(PG8_SB(0, 0), cB, voffB); PG8_STAGE(PG8_SA(0, 0), cA, voffA); PG8_STAGE(PG8_SB(0, 1), cB + hstep, voffB); PG8_STAGE(PG8_SA(0, 1), cA + hstep, voffA);
;         if (wr == 1) PG8_BAR;
;         PG8_WAIT_V(4); PG8_BAR;
;         PG8_STAGE(PG8_SB(1, 0), cB + kstep, voffB); PG8_STAGE(PG8_SA(1, 0), cA + kstep, voffA); PG8_STAGE(PG8_SB(1, 1), cB + hstep + kstep, voffB);
;         PG8_WAIT_V(6); PG8_BAR;
.LBB0_704:
.LBB0_705:
	s_xor_b64 s[36:37], s[4:5], -1
	s_add_u32 s33, s14, 0x1200000
	v_lshlrev_b32_e32 v2, 4, v0
	s_addc_u32 s54, s15, 0
	v_and_b32_e32 v3, 32, v0
	s_waitcnt vmcnt(0)
	v_or_b32_e32 v146, 0x2000, v2
	s_add_u32 s55, s14, 0x1000000
	v_bfe_u32 v1, v0, 2, 4
	v_bitop3_b32 v144, v2, v3, 48 bitop3:0x6c
	v_and_b32_e32 v145, 64, v0
	v_lshrrev_b32_e32 v2, 7, v146
	s_movk_i32 s2, 0x70
	s_addc_u32 s56, s15, 0
	v_or_b32_e32 v3, v144, v145
	v_lshrrev_b32_e32 v4, 3, v0
	v_and_or_b32 v2, v2, s2, v1
	v_and_b32_e32 v142, 15, v0
	s_lshl_b32 s2, s34, 4
	s_lshr_b32 s26, s34, 8
	v_and_or_b32 v4, v4, 48, v1
	v_lshl_or_b32 v132, v2, 11, v3
	s_and_b32 s57, s2, 0xfffffc00
	s_lshr_b32 s2, s34, 1
	v_mov_b32_e32 v2, v142
	s_mov_b32 s7, 0
	s_ashr_i32 s31, s30, 31
	s_lshl_b32 s8, s28, 8
	v_lshl_or_b32 v130, v4, 11, v3
	s_lshl_b32 s4, s26, 6
	s_and_b32 s27, s2, 0x60
	s_mov_b32 s5, s7
	v_ashrrev_i32_e32 v3, 31, v2
	s_ashr_i32 s9, s8, 31
	s_lshl_b64 s[10:11], s[30:31], 20
	v_bfe_u32 v143, v0, 4, 2
	v_lshl_add_u64 v[2:3], v[2:3], 0, s[4:5]
	s_add_u32 s10, s16, s10
	v_mov_b32_e32 v4, v143
	v_lshlrev_b64 v[2:3], 12, v[2:3]
	s_addc_u32 s11, s17, s11
	s_lshl_b64 s[84:85], s[8:9], 2
	s_add_u32 s84, s84, s10
	s_addc_u32 s85, s85, s11
	v_lshl_add_u64 v[2:3], s[10:11], 0, v[2:3]
	v_lshlrev_b32_e32 v4, 2, v4
	v_lshl_add_u64 v[2:3], s[8:9], 2, v[2:3]
	s_lshl_b32 s6, s27, 2
	v_ashrrev_i32_e32 v5, 31, v4
	v_lshl_add_u64 v[2:3], v[2:3], 0, s[6:7]
	v_lshl_add_u64 v[114:115], v[4:5], 2, v[2:3]
	v_add_u32_e32 v234, s4, v142
	v_lshlrev_b32_e32 v234, 12, v234
	v_lshl_add_u32 v234, v143, 4, v234
	v_add_u32_e32 v234, s6, v234
	v_mov_b32_e32 v235, 0
	s_mov_b32 s58, 0x10000
	v_add_co_u32_e32 v36, vcc, s58, v114
	s_mov_b32 s59, 0x20000
	s_nop 0
	v_addc_co_u32_e32 v37, vcc, 0, v115, vcc
	v_add_co_u32_e32 v52, vcc, s59, v114
	s_mov_b32 s60, 0x30000
	s_nop 0
	v_addc_co_u32_e32 v53, vcc, 0, v115, vcc
	v_add_co_u32_e32 v68, vcc, s60, v114
	s_mov_b32 s61, 0x80000
	s_nop 0
	v_addc_co_u32_e32 v69, vcc, 0, v115, vcc
	v_add_co_u32_e32 v84, vcc, s61, v114
	s_mov_b32 s62, 0x90000
	s_nop 0
	v_addc_co_u32_e32 v85, vcc, 0, v115, vcc
	v_add_co_u32_e32 v100, vcc, s62, v114
	s_mov_b32 s63, 0xa0000
	s_nop 0
	v_addc_co_u32_e32 v101, vcc, 0, v115, vcc
	s_ashr_i32 s29, s28, 31
	s_mov_b64 s[8:9], 0x10000
	s_mov_b64 s[10:11], 0x20000
	s_mov_b64 s[12:13], 0x30000
	s_mov_b64 s[14:15], 0x80000
	s_mov_b64 s[18:19], 0x90000
	s_mov_b64 s[20:21], 0xa0000
	v_add_co_u32_e32 v118, vcc, s63, v114
	s_lshl_b64 s[24:25], s[30:31], 19
	s_lshl_b64 s[40:41], s[28:29], 19
	v_lshl_add_u64 v[34:35], v[114:115], 0, s[8:9]
	v_lshl_add_u64 v[50:51], v[114:115], 0, s[10:11]
	v_lshl_add_u64 v[66:67], v[114:115], 0, s[12:13]
	v_lshl_add_u64 v[82:83], v[114:115], 0, s[14:15]
	v_lshl_add_u64 v[98:99], v[114:115], 0, s[18:19]
	v_lshl_add_u64 v[116:117], v[114:115], 0, s[20:21]
	v_addc_co_u32_e32 v119, vcc, 0, v115, vcc
	s_mov_b32 s2, 0xb0000
	s_add_u32 s46, s55, s40
	s_mov_b64 s[22:23], 0xb0000
	v_add_co_u32_e32 v118, vcc, s2, v114
	s_addc_u32 s47, s56, s41
	s_add_i32 s64, s57, 0
	v_lshl_add_u64 v[126:127], v[114:115], 0, s[22:23]
	v_addc_co_u32_e32 v119, vcc, 0, v115, vcc
	s_add_i32 m0, s64, 0x10000
	v_mov_b32_e32 v131, 0
	global_load_lds_dwordx4 v130, s[46:47]
	s_add_i32 m0, s64, 0x12000
	s_add_u32 s40, s46, 0x40000
	global_load_lds_dwordx4 v132, s[46:47]
	s_addc_u32 s41, s47, 0
	s_add_i32 m0, s64, 0x14000
	v_mov_b32_e32 v133, v131
	global_load_lds_dwordx4 v130, s[40:41]
	s_add_i32 m0, s64, 0x16000
	s_add_u32 s48, s33, s24
	s_addc_u32 s49, s54, s25
	s_add_i32 s65, s64, 0x2000
	global_load_lds_dwordx4 v132, s[40:41]
	s_mov_b32 m0, s64
	s_add_u32 s24, s48, 0x40000
	global_load_lds_dwordx4 v130, s[48:49]
	s_mov_b32 m0, s65
	s_addc_u32 s25, s49, 0
	s_add_i32 s66, s64, 0x4000
	global_load_lds_dwordx4 v132, s[48:49]
	s_mov_b32 m0, s66
	s_add_i32 s67, s64, 0x6000
	global_load_lds_dwordx4 v130, s[24:25]
	s_mov_b32 m0, s67
	s_cmp_eq_u32 s26, 1
	global_load_lds_dwordx4 v132, s[24:25]
	v_lshl_add_u64 v[140:141], s[46:47], 0, v[130:131]
	v_lshl_add_u64 v[138:139], s[46:47], 0, v[132:133]
	v_lshl_add_u64 v[134:135], s[48:49], 0, v[130:131]
	s_cselect_b64 s[24:25], -1, 0
	s_cmp_lg_u32 s26, 1
	v_lshl_add_u64 v[136:137], s[48:49], 0, v[132:133]
	s_cbranch_scc1 .LBB0_707
	s_barrier

; #define PG8_STAGE(bufoff, gbase, voff) do { _Pragma("unroll") for (int _i = 0; _i < 2; ++_i) \
;         __builtin_amdgcn_global_load_lds((const unsigned*)((const char*)(gbase) + (voff)[_i]), (PG8_LAS unsigned*)(lds + (bufoff) + ldsw + _i * 8192), 16, 0, 0); } while (0)
; #define PG8_LDA(dst, b, h) do { _Pragma("unroll") for (int m = 0; m < 4; ++m) _Pragma("unroll") for (int k = 0; k < 2; ++k) dst[m][k] = *(const PG8_LAS bf16x8*)(lds + PG8_SA(b, h) + aoff + m * 2048 + k * 1024); } while (0)
;     __device__ __forceinline__ void init(f32x4 (&acc)[2][2][4][2], const Unit& u, int wr, int wc, int fr, int fq) const {
;     ...
;             for (int m = 0; m < 4; ++m) { const size_t off = ((size_t)u.pm * 256 + 128 * ai + 64 * wr + 16 * m + fr) * DM + u.pn * 256 + 32 * wc + 4 * fq;
; #pragma unroll
;                 for (int bj = 0; bj < 2; ++bj)
; #pragma unroll
;                     for (int n = 0; n < 2; ++n) acc[ai][bj][m][n] = __builtin_nontemporal_load((const f32x4*)(x + off + bj * HALF + n * 16)); }
; template <class Epi, class Sched, bool ALIGN_EPI = false, bool SP2 = false>
; __device__ __forceinline__ void gemm_phase(PG8_LAS unsigned char* lds, const Gemm g, const Sched& S, const Epi& E) {
;     ...
;         const bool has_next = S.next(ui + 1, nxt);
;         const char* nA = has_next ? (const char*)g.A + (size_t)nxt.pm * tstep : cA; const char* nB = has_next ? (const char*)g.Bt + (size_t)nxt.pn * tstep : cB;
;         for (int t = 0; t < nt; t += 2) {
;             if constexpr (Epi::HAS_MID) { if (t == nt / 2) E.mid(acc, cur, wr, wc, fr, fq); }
;             const bool last = (t == nt - 2);
;             const char* a1 = cA + (size_t)(t + 1) * kstep;
;             const char* a2 = last ? nA : cA + (size_t)(t + 2) * kstep; const char* b2 = last ? nB : cB + (size_t)(t + 2) * kstep;
;             const char* a3 = a2 + kstep; const char* b3 = b2 + kstep;
;             if (last && has_next) S.a_ready(nxt);
;             if constexpr (SP2) {
;             PG8_LDB(B0, 0, 0); PG8_LDB(B1, 0, 1); PG8_SCHED; PG8_LDA(At, 0, 0); PG8_STAGE(PG8_SA(1, 1), a1 + hstep, voffA);
;             PG8_WAIT_V(8); PG8_WAIT_L(0); PG8_BAR; PG8_MMA(0, 0, At, B0); PG8_MMA(0, 1, At, B1); PG8_BAR; PG8_SCHED;
;             PG8_LDA(At, 0, 1); PG8_STAGE(PG8_SB(0, 0), b2, voffB); PG8_STAGE(PG8_SB(0, 1), b2 + hstep, voffB); PG8_STAGE(PG8_SA(0, 0), a2, voffA);
.LBB0_721:
	s_mov_b32 s36, s31
	s_mov_b32 s38, s37
	s_ashr_i32 s37, s31, 31
	s_lshl_b64 s[40:41], s[36:37], 19
	s_add_u32 s40, s33, s40
	s_addc_u32 s41, s54, s41
	s_and_b64 s[42:43], s[44:45], exec
	s_cselect_b32 s29, s41, s49
	s_cselect_b32 s31, s40, s48
	s_ashr_i32 s39, s38, 31
	s_lshl_b64 s[42:43], s[38:39], 19
	s_add_u32 s42, s55, s42
	s_addc_u32 s43, s56, s43
	s_and_b64 s[52:53], s[44:45], exec
	s_cselect_b32 s39, s43, s47
	s_cselect_b32 s77, s42, s46
	s_add_u32 s48, s48, 0x40080
	s_addc_u32 s49, s49, 0
	s_add_u32 s78, s46, 0x100
	s_addc_u32 s79, s47, 0
	s_mov_b32 s80, -2
	s_lshl_b64 s[86:87], s[36:37], 20
	s_add_u32 s86, s86, s16
	s_addc_u32 s87, s87, s17
	s_lshl_b32 s88, s38, 10
	s_add_u32 s86, s86, s88
	s_addc_u32 s87, s87, 0
	v_add_u32_e32 v140, s74, v138
	ds_read_b128 v[144:147], v140
	ds_read_b128 v[148:151], v140 offset:1024
	ds_read_b128 v[152:155], v140 offset:2048
	ds_read_b128 v[156:159], v140 offset:3072
	v_add_u32_e32 v140, s75, v138
	ds_read_b128 v[160:163], v140
	ds_read_b128 v[164:167], v140 offset:1024
	ds_read_b128 v[168:171], v140 offset:2048
	ds_read_b128 v[172:175], v140 offset:3072
	s_add_u32 s2, s48, 0xfffc0080
	s_addc_u32 s46, s49, -1
	s_cmp_eq_u32 s80, 12
	s_cselect_b32 s53, s29, s46
	s_cselect_b32 s52, s31, s2
	s_cselect_b32 s47, s39, s79
	s_cselect_b32 s46, s77, s78
	v_lshl_add_u64 v[140:141], s[48:49], 0, v[0:1]
	s_add_i32 m0, s64, 0xc000
	ds_read_b128 v[176:179], v139
	ds_read_b128 v[180:183], v139 offset:1024
	ds_read_b128 v[184:187], v139 offset:2048
	ds_read_b128 v[188:191], v139 offset:3072
	ds_read_b128 v[192:195], v139 offset:4096
	ds_read_b128 v[196:199], v139 offset:5120
	ds_read_b128 v[200:203], v139 offset:6144
	ds_read_b128 v[204:207], v139 offset:7168
	global_load_lds_dwordx4 v[140:141], off
	v_lshl_add_u64 v[140:141], s[48:49], 0, v[134:135]
	s_add_i32 m0, s64, 0xe000
	s_nop 0
	global_load_lds_dwordx4 v[140:141], off
	s_waitcnt vmcnt(12)
	s_waitcnt lgkmcnt(0)
	s_barrier
	s_setprio 1
	s_waitcnt lgkmcnt(0)
	v_mfma_f32_16x16x32_bf16 v[2:5], v[144:147], v[176:179], 0
	v_mfma_f32_16x16x32_bf16 v[6:9], v[152:155], v[176:179], 0
	v_mfma_f32_16x16x32_bf16 v[22:25], v[144:147], v[184:187], 0
	v_mfma_f32_16x16x32_bf16 v[18:21], v[152:155], v[184:187], 0
	v_mfma_f32_16x16x32_bf16 v[38:41], v[144:147], v[192:195], 0
	v_mfma_f32_16x16x32_bf16 v[34:37], v[152:155], v[192:195], 0
	v_mfma_f32_16x16x32_bf16 v[54:57], v[144:147], v[200:203], 0
	v_mfma_f32_16x16x32_bf16 v[50:53], v[152:155], v[200:203], 0
	v_mfma_f32_16x16x32_bf16 v[2:5], v[148:151], v[180:183], v[2:5]
	v_mfma_f32_16x16x32_bf16 v[6:9], v[156:159], v[180:183], v[6:9]
	v_mfma_f32_16x16x32_bf16 v[22:25], v[148:151], v[188:191], v[22:25]
	v_mfma_f32_16x16x32_bf16 v[18:21], v[156:159], v[188:191], v[18:21]
	v_mfma_f32_16x16x32_bf16 v[38:41], v[148:151], v[196:199], v[38:41]
	v_mfma_f32_16x16x32_bf16 v[34:37], v[156:159], v[196:199], v[34:37]
	v_mfma_f32_16x16x32_bf16 v[54:57], v[148:151], v[204:207], v[54:57]
	v_mfma_f32_16x16x32_bf16 v[50:53], v[156:159], v[204:207], v[50:53]
	v_mfma_f32_16x16x32_bf16 v[10:13], v[160:163], v[176:179], 0
	v_mfma_f32_16x16x32_bf16 v[14:17], v[168:171], v[176:179], 0
	v_mfma_f32_16x16x32_bf16 v[26:29], v[160:163], v[184:187], 0
	v_mfma_f32_16x16x32_bf16 v[30:33], v[168:171], v[184:187], 0
	v_mfma_f32_16x16x32_bf16 v[42:45], v[160:163], v[192:195], 0
	v_mfma_f32_16x16x32_bf16 v[46:49], v[168:171], v[192:195], 0
	v_mfma_f32_16x16x32_bf16 v[58:61], v[160:163], v[200:203], 0
	v_mfma_f32_16x16x32_bf16 v[62:65], v[168:171], v[200:203], 0
	v_mfma_f32_16x16x32_bf16 v[10:13], v[164:167], v[180:183], v[10:13]
	v_mfma_f32_16x16x32_bf16 v[14:17], v[172:175], v[180:183], v[14:17]
	v_mfma_f32_16x16x32_bf16 v[26:29], v[164:167], v[188:191], v[26:29]
	v_mfma_f32_16x16x32_bf16 v[30:33], v[172:175], v[188:191], v[30:33]
	v_mfma_f32_16x16x32_bf16 v[42:45], v[164:167], v[196:199], v[42:45]
	v_mfma_f32_16x16x32_bf16 v[46:49], v[172:175], v[196:199], v[46:49]
	v_mfma_f32_16x16x32_bf16 v[58:61], v[164:167], v[204:207], v[58:61]
	v_mfma_f32_16x16x32_bf16 v[62:65], v[172:175], v[204:207], v[62:65]
	s_setprio 0
	s_barrier
	s_add_i32 s2, s74, s57
	v_lshl_add_u64 v[140:141], s[46:47], 0, v[130:131]
	s_mov_b32 m0, s2
	ds_read_b128 v[176:179], v139 offset:16384
	ds_read_b128 v[180:183], v139 offset:17408
	ds_read_b128 v[184:187], v139 offset:18432
	ds_read_b128 v[188:191], v139 offset:19456
	ds_read_b128 v[192:195], v139 offset:20480
	ds_read_b128 v[196:199], v139 offset:21504
	ds_read_b128 v[200:203], v139 offset:22528
	ds_read_b128 v[204:207], v139 offset:23552
	global_load_lds_dwordx4 v[140:141], off
	s_add_i32 m0, s2, 0x2000
	s_add_u32 s82, s46, 0x40000
	v_lshl_add_u64 v[208:209], s[46:47], 0, v[132:133]
	s_addc_u32 s83, s47, 0
	s_add_i32 s2, s75, s57
	global_load_lds_dwordx4 v[208:209], off
	v_lshl_add_u64 v[210:211], s[82:83], 0, v[130:131]
	s_mov_b32 m0, s2
	v_lshl_add_u64 v[212:213], s[52:53], 0, v[132:133]
	global_load_lds_dwordx4 v[210:211], off
	v_lshl_add_u64 v[210:211], s[82:83], 0, v[132:133]
	s_add_i32 m0, s2, 0x2000
	s_nop 0
	global_load_lds_dwordx4 v[210:211], off
	v_lshl_add_u64 v[210:211], s[52:53], 0, v[130:131]
	s_mov_b32 m0, s64
	s_nop 0
	global_load_lds_dwordx4 v[210:211], off
	s_mov_b32 m0, s65
	s_nop 0
	global_load_lds_dwordx4 v[212:213], off
	s_waitcnt vmcnt(12)
	s_waitcnt lgkmcnt(0)
	s_barrier
; #define PG8_STAGE(bufoff, gbase, voff) do { _Pragma("unroll") for (int _i = 0; _i < 2; ++_i) \
;         __builtin_amdgcn_global_load_lds((const unsigned*)((const char*)(gbase) + (voff)[_i]), (PG8_LAS unsigned*)(lds + (bufoff) + ldsw + _i * 8192), 16, 0, 0); } while (0)
; #define PG8_LDA(dst, b, h) do { _Pragma("unroll") for (int m = 0; m < 4; ++m) _Pragma("unroll") for (int k = 0; k < 2; ++k) dst[m][k] = *(const PG8_LAS bf16x8*)(lds + PG8_SA(b, h) + aoff + m * 2048 + k * 1024); } while (0)
; #define PG8_LDB(dst, b, h) do { _Pragma("unroll") for (int n = 0; n < 2; ++n) _Pragma("unroll") for (int k = 0; k < 2; ++k) dst[n][k] = *(const PG8_LAS bf16x8*)(lds + PG8_SB(b, h) + boff + n * 2048 + k * 1024); } while (0)
; #define PG8_MMA(ai, bj, At, Bt) do { __builtin_amdgcn_s_setprio(1); _Pragma("unroll") for (int m = 0; m < 4; ++m) _Pragma("unroll") for (int n = 0; n < 2; ++n) _Pragma("unroll") for (int k = 0; k < 2; ++k) \
;         acc[ai][bj][m][n] = __builtin_amdgcn_mfma_f32_16x16x32_bf16(Bt[n][k], At[m][k], acc[ai][bj][m][n], 0, 0, 0); __builtin_amdgcn_s_setprio(0); } while (0)
; #define PG8_WAIT_V(n) asm volatile("s_waitcnt vmcnt(" #n ")" ::: "memory")
; #define PG8_WAIT_L(n) asm volatile("s_waitcnt lgkmcnt(" #n ")" ::: "memory")
; #define PG8_BAR __builtin_amdgcn_s_barrier()
; #define PG8_SCHED __builtin_amdgcn_sched_barrier(0)
; template <class Epi, class Sched, bool ALIGN_EPI = false, bool SP2 = false>
; __device__ __forceinline__ void gemm_phase(PG8_LAS unsigned char* lds, const Gemm g, const Sched& S, const Epi& E) {
;     ...
;             PG8_LDA(At, 0, 1); PG8_STAGE(PG8_SB(0, 0), b2, voffB); PG8_STAGE(PG8_SB(0, 1), b2 + hstep, voffB); PG8_STAGE(PG8_SA(0, 0), a2, voffA);
;             PG8_WAIT_V(8); PG8_WAIT_L(0); PG8_BAR; PG8_MMA(1, 0, At, B0); PG8_MMA(1, 1, At, B1); PG8_BAR; PG8_SCHED;
;             PG8_LDB(B0, 1, 0); PG8_LDB(B1, 1, 1); PG8_SCHED; PG8_LDA(At, 1, 0); PG8_STAGE(PG8_SA(0, 1), a2 + hstep, voffA);
;             PG8_WAIT_V(8); PG8_WAIT_L(0); PG8_BAR; PG8_MMA(0, 0, At, B0); PG8_MMA(0, 1, At, B1); PG8_BAR; PG8_SCHED;
	s_setprio 1
	s_waitcnt lgkmcnt(0)
	v_mfma_f32_16x16x32_bf16 v[70:73], v[144:147], v[176:179], 0
	v_mfma_f32_16x16x32_bf16 v[66:69], v[152:155], v[176:179], 0
	v_mfma_f32_16x16x32_bf16 v[86:89], v[144:147], v[184:187], 0
	v_mfma_f32_16x16x32_bf16 v[82:85], v[152:155], v[184:187], 0
	v_mfma_f32_16x16x32_bf16 v[102:105], v[144:147], v[192:195], 0
	v_mfma_f32_16x16x32_bf16 v[98:101], v[152:155], v[192:195], 0
	v_mfma_f32_16x16x32_bf16 v[118:121], v[144:147], v[200:203], 0
	v_mfma_f32_16x16x32_bf16 v[114:117], v[152:155], v[200:203], 0
	v_mfma_f32_16x16x32_bf16 v[70:73], v[148:151], v[180:183], v[70:73]
	v_mfma_f32_16x16x32_bf16 v[66:69], v[156:159], v[180:183], v[66:69]
	v_mfma_f32_16x16x32_bf16 v[86:89], v[148:151], v[188:191], v[86:89]
	v_mfma_f32_16x16x32_bf16 v[82:85], v[156:159], v[188:191], v[82:85]
	v_mfma_f32_16x16x32_bf16 v[102:105], v[148:151], v[196:199], v[102:105]
	v_mfma_f32_16x16x32_bf16 v[98:101], v[156:159], v[196:199], v[98:101]
	v_mfma_f32_16x16x32_bf16 v[118:121], v[148:151], v[204:207], v[118:121]
	v_mfma_f32_16x16x32_bf16 v[114:117], v[156:159], v[204:207], v[114:117]
	v_mfma_f32_16x16x32_bf16 v[74:77], v[160:163], v[176:179], 0
	v_mfma_f32_16x16x32_bf16 v[78:81], v[168:171], v[176:179], 0
	v_mfma_f32_16x16x32_bf16 v[90:93], v[160:163], v[184:187], 0
	v_mfma_f32_16x16x32_bf16 v[94:97], v[168:171], v[184:187], 0
	v_mfma_f32_16x16x32_bf16 v[106:109], v[160:163], v[192:195], 0
	v_mfma_f32_16x16x32_bf16 v[110:113], v[168:171], v[192:195], 0
	v_mfma_f32_16x16x32_bf16 v[122:125], v[160:163], v[200:203], 0
	v_mfma_f32_16x16x32_bf16 v[126:129], v[168:171], v[200:203], 0
	v_mfma_f32_16x16x32_bf16 v[74:77], v[164:167], v[180:183], v[74:77]
	v_mfma_f32_16x16x32_bf16 v[78:81], v[172:175], v[180:183], v[78:81]
	v_mfma_f32_16x16x32_bf16 v[90:93], v[164:167], v[188:191], v[90:93]
	v_mfma_f32_16x16x32_bf16 v[94:97], v[172:175], v[188:191], v[94:97]
	v_mfma_f32_16x16x32_bf16 v[106:109], v[164:167], v[196:199], v[106:109]
	v_mfma_f32_16x16x32_bf16 v[110:113], v[172:175], v[196:199], v[110:113]
	v_mfma_f32_16x16x32_bf16 v[122:125], v[164:167], v[204:207], v[122:125]
	v_mfma_f32_16x16x32_bf16 v[126:129], v[172:175], v[204:207], v[126:129]
	s_setprio 0
	s_barrier
	s_add_i32 s2, 0, 0x18000
	s_add_i32 s81, 0, 0x1c000
	v_add_u32_e32 v156, s2, v138
	v_add_u32_e32 v172, s81, v138
	ds_read_b128 v[144:147], v156
	ds_read_b128 v[148:151], v156 offset:1024
	ds_read_b128 v[152:155], v156 offset:2048
	ds_read_b128 v[156:159], v156 offset:3072
	ds_read_b128 v[160:163], v172
	ds_read_b128 v[164:167], v172 offset:1024
	ds_read_b128 v[168:171], v172 offset:2048
	ds_read_b128 v[172:175], v172 offset:3072
	s_add_u32 s52, s52, 0x40000
	s_addc_u32 s53, s53, 0
	s_mov_b32 m0, s66
	v_lshl_add_u64 v[214:215], s[52:53], 0, v[130:131]
	ds_read_b128 v[176:179], v139 offset:32768
	ds_read_b128 v[180:183], v139 offset:33792
	ds_read_b128 v[184:187], v139 offset:34816
	ds_read_b128 v[188:191], v139 offset:35840
	ds_read_b128 v[192:195], v139 offset:36864
	ds_read_b128 v[196:199], v139 offset:37888
	ds_read_b128 v[200:203], v139 offset:38912
	ds_read_b128 v[204:207], v139 offset:39936
	global_load_lds_dwordx4 v[214:215], off
	v_lshl_add_u64 v[214:215], s[52:53], 0, v[132:133]
	s_mov_b32 m0, s67
	s_nop 0
	global_load_lds_dwordx4 v[214:215], off
	s_waitcnt vmcnt(8)
	s_waitcnt lgkmcnt(0)
	s_barrier
; #define PG8_STAGE(bufoff, gbase, voff) do { _Pragma("unroll") for (int _i = 0; _i < 2; ++_i) \
;         __builtin_amdgcn_global_load_lds((const unsigned*)((const char*)(gbase) + (voff)[_i]), (PG8_LAS unsigned*)(lds + (bufoff) + ldsw + _i * 8192), 16, 0, 0); } while (0)
; #define PG8_LDA(dst, b, h) do { _Pragma("unroll") for (int m = 0; m < 4; ++m) _Pragma("unroll") for (int k = 0; k < 2; ++k) dst[m][k] = *(const PG8_LAS bf16x8*)(lds + PG8_SA(b, h) + aoff + m * 2048 + k * 1024); } while (0)
; #define PG8_MMA(ai, bj, At, Bt) do { __builtin_amdgcn_s_setprio(1); _Pragma("unroll") for (int m = 0; m < 4; ++m) _Pragma("unroll") for (int n = 0; n < 2; ++n) _Pragma("unroll") for (int k = 0; k < 2; ++k) \
;         acc[ai][bj][m][n] = __builtin_amdgcn_mfma_f32_16x16x32_bf16(Bt[n][k], At[m][k], acc[ai][bj][m][n], 0, 0, 0); __builtin_amdgcn_s_setprio(0); } while (0)
; #define PG8_WAIT_V(n) asm volatile("s_waitcnt vmcnt(" #n ")" ::: "memory")
; #define PG8_WAIT_L(n) asm volatile("s_waitcnt lgkmcnt(" #n ")" ::: "memory")
; #define PG8_BAR __builtin_amdgcn_s_barrier()
; #define PG8_SCHED __builtin_amdgcn_sched_barrier(0)
;     __device__ __forceinline__ void init(f32x4 (&acc)[2][2][4][2], const Unit& u, int wr, int wc, int fr, int fq) const {
;     ...
; #pragma unroll
;         for (int ai = 0; ai < 2; ++ai)
; #pragma unroll
;             for (int m = 0; m < 4; ++m) { const size_t off = ((size_t)u.pm * 256 + 128 * ai + 64 * wr + 16 * m + fr) * DM + u.pn * 256 + 32 * wc + 4 * fq;
; #pragma unroll
;                 for (int bj = 0; bj < 2; ++bj)
; #pragma unroll
;                     for (int n = 0; n < 2; ++n) acc[ai][bj][m][n] = __builtin_nontemporal_load((const f32x4*)(x + off + bj * HALF + n * 16)); }
; template <class Epi, class Sched, bool ALIGN_EPI = false, bool SP2 = false>
; __device__ __forceinline__ void gemm_phase(PG8_LAS unsigned char* lds, const Gemm g, const Sched& S, const Epi& E) {
;     ...
;             PG8_LDA(At, 1, 1); PG8_STAGE(PG8_SB(1, 0), b3, voffB); PG8_STAGE(PG8_SB(1, 1), b3 + hstep, voffB); PG8_STAGE(PG8_SA(1, 0), a3, voffA);
;             PG8_WAIT_V(8); PG8_WAIT_L(0); PG8_BAR; PG8_MMA(1, 0, At, B0); PG8_MMA(1, 1, At, B1); PG8_BAR; PG8_SCHED;
	s_setprio 1
	s_waitcnt lgkmcnt(0)
	v_mfma_f32_16x16x32_bf16 v[2:5], v[144:147], v[176:179], v[2:5]
	v_mfma_f32_16x16x32_bf16 v[6:9], v[152:155], v[176:179], v[6:9]
	v_mfma_f32_16x16x32_bf16 v[22:25], v[144:147], v[184:187], v[22:25]
	v_mfma_f32_16x16x32_bf16 v[18:21], v[152:155], v[184:187], v[18:21]
	v_mfma_f32_16x16x32_bf16 v[38:41], v[144:147], v[192:195], v[38:41]
	v_mfma_f32_16x16x32_bf16 v[34:37], v[152:155], v[192:195], v[34:37]
	v_mfma_f32_16x16x32_bf16 v[54:57], v[144:147], v[200:203], v[54:57]
	v_mfma_f32_16x16x32_bf16 v[50:53], v[152:155], v[200:203], v[50:53]
	v_mfma_f32_16x16x32_bf16 v[2:5], v[148:151], v[180:183], v[2:5]
	v_mfma_f32_16x16x32_bf16 v[6:9], v[156:159], v[180:183], v[6:9]
	v_mfma_f32_16x16x32_bf16 v[22:25], v[148:151], v[188:191], v[22:25]
	v_mfma_f32_16x16x32_bf16 v[18:21], v[156:159], v[188:191], v[18:21]
	v_mfma_f32_16x16x32_bf16 v[38:41], v[148:151], v[196:199], v[38:41]
	v_mfma_f32_16x16x32_bf16 v[34:37], v[156:159], v[196:199], v[34:37]
	v_mfma_f32_16x16x32_bf16 v[54:57], v[148:151], v[204:207], v[54:57]
	v_mfma_f32_16x16x32_bf16 v[50:53], v[156:159], v[204:207], v[50:53]
	v_mfma_f32_16x16x32_bf16 v[10:13], v[160:163], v[176:179], v[10:13]
	v_mfma_f32_16x16x32_bf16 v[14:17], v[168:171], v[176:179], v[14:17]
	v_mfma_f32_16x16x32_bf16 v[26:29], v[160:163], v[184:187], v[26:29]
	v_mfma_f32_16x16x32_bf16 v[30:33], v[168:171], v[184:187], v[30:33]
	v_mfma_f32_16x16x32_bf16 v[42:45], v[160:163], v[192:195], v[42:45]
	v_mfma_f32_16x16x32_bf16 v[46:49], v[168:171], v[192:195], v[46:49]
	v_mfma_f32_16x16x32_bf16 v[58:61], v[160:163], v[200:203], v[58:61]
	v_mfma_f32_16x16x32_bf16 v[62:65], v[168:171], v[200:203], v[62:65]
	v_mfma_f32_16x16x32_bf16 v[10:13], v[164:167], v[180:183], v[10:13]
	v_mfma_f32_16x16x32_bf16 v[14:17], v[172:175], v[180:183], v[14:17]
	v_mfma_f32_16x16x32_bf16 v[26:29], v[164:167], v[188:191], v[26:29]
	v_mfma_f32_16x16x32_bf16 v[30:33], v[172:175], v[188:191], v[30:33]
	v_mfma_f32_16x16x32_bf16 v[42:45], v[164:167], v[196:199], v[42:45]
	v_mfma_f32_16x16x32_bf16 v[46:49], v[172:175], v[196:199], v[46:49]
	v_mfma_f32_16x16x32_bf16 v[58:61], v[164:167], v[204:207], v[58:61]
	v_mfma_f32_16x16x32_bf16 v[62:65], v[172:175], v[204:207], v[62:65]
	s_setprio 0
	s_barrier
	s_add_i32 s2, s2, s57
	v_lshl_add_u64 v[140:141], v[140:141], 0, s[26:27]
	s_mov_b32 m0, s2
	ds_read_b128 v[176:179], v139 offset:49152
	ds_read_b128 v[180:183], v139 offset:50176
	ds_read_b128 v[184:187], v139 offset:51200
	ds_read_b128 v[188:191], v139 offset:52224
	ds_read_b128 v[192:195], v139 offset:53248
	ds_read_b128 v[196:199], v139 offset:54272
	ds_read_b128 v[200:203], v139 offset:55296
	ds_read_b128 v[204:207], v139 offset:56320
	global_load_lds_dwordx4 v[140:141], off
	s_add_i32 m0, s2, 0x2000
	s_add_u32 s46, s46, 0x40080
	v_lshl_add_u64 v[140:141], v[208:209], 0, s[26:27]
	s_addc_u32 s47, s47, 0
	s_add_i32 s2, s81, s57
	global_load_lds_dwordx4 v[140:141], off
	v_lshl_add_u64 v[140:141], s[46:47], 0, v[130:131]
	s_mov_b32 m0, s2
	s_nop 0
	global_load_lds_dwordx4 v[140:141], off
	v_lshl_add_u64 v[140:141], s[46:47], 0, v[132:133]
	s_add_i32 m0, s2, 0x2000
	s_nop 0
	global_load_lds_dwordx4 v[140:141], off
	v_lshl_add_u64 v[140:141], v[210:211], 0, s[26:27]
	s_mov_b32 m0, s68
	s_nop 0
	global_load_lds_dwordx4 v[140:141], off
	v_lshl_add_u64 v[140:141], v[212:213], 0, s[26:27]
	s_mov_b32 m0, s69
	s_nop 0
	global_load_lds_dwordx4 v[140:141], off
	s_cmp_lt_i32 s80, 6
	s_cbranch_scc0 .Lxa_hi_pl
	s_cmp_lt_i32 s80, 2
	s_cbranch_scc0 .Lxa_23_pl
	s_cmp_lt_i32 s80, 0
	s_cbranch_scc0 .Lxa_1_pl
	v_add_f32_e32 v2, v2, v216
	v_add_f32_e32 v3, v3, v217
	v_add_f32_e32 v4, v4, v218
	v_add_f32_e32 v5, v5, v219
	v_add_f32_e32 v6, v6, v220
	v_add_f32_e32 v7, v7, v221
	v_add_f32_e32 v8, v8, v222
	v_add_f32_e32 v9, v9, v223
	v_add_f32_e32 v10, v10, v224
	v_add_f32_e32 v11, v11, v225
	v_add_f32_e32 v12, v12, v226
	v_add_f32_e32 v13, v13, v227
	v_add_f32_e32 v14, v14, v228
	v_add_f32_e32 v15, v15, v229
	v_add_f32_e32 v16, v16, v230
	v_add_f32_e32 v17, v17, v231
	s_branch .Lxa_done_pl

; #define PG8_STAGE(bufoff, gbase, voff) do { _Pragma("unroll") for (int _i = 0; _i < 2; ++_i) \
;         __builtin_amdgcn_global_load_lds((const unsigned*)((const char*)(gbase) + (voff)[_i]), (PG8_LAS unsigned*)(lds + (bufoff) + ldsw + _i * 8192), 16, 0, 0); } while (0)
; #define PG8_LDA(dst, b, h) do { _Pragma("unroll") for (int m = 0; m < 4; ++m) _Pragma("unroll") for (int k = 0; k < 2; ++k) dst[m][k] = *(const PG8_LAS bf16x8*)(lds + PG8_SA(b, h) + aoff + m * 2048 + k * 1024); } while (0)
; #define PG8_MMA(ai, bj, At, Bt) do { __builtin_amdgcn_s_setprio(1); _Pragma("unroll") for (int m = 0; m < 4; ++m) _Pragma("unroll") for (int n = 0; n < 2; ++n) _Pragma("unroll") for (int k = 0; k < 2; ++k) \
;         acc[ai][bj][m][n] = __builtin_amdgcn_mfma_f32_16x16x32_bf16(Bt[n][k], At[m][k], acc[ai][bj][m][n], 0, 0, 0); __builtin_amdgcn_s_setprio(0); } while (0)
; #define PG8_WAIT_V(n) asm volatile("s_waitcnt vmcnt(" #n ")" ::: "memory")
; #define PG8_WAIT_L(n) asm volatile("s_waitcnt lgkmcnt(" #n ")" ::: "memory")
; #define PG8_BAR __builtin_amdgcn_s_barrier()
; #define PG8_SCHED __builtin_amdgcn_sched_barrier(0)
;     __device__ __forceinline__ void init(f32x4 (&acc)[2][2][4][2], const Unit& u, int wr, int wc, int fr, int fq) const {
;     ...
; #pragma unroll
;         for (int ai = 0; ai < 2; ++ai)
; #pragma unroll
;             for (int m = 0; m < 4; ++m) { const size_t off = ((size_t)u.pm * 256 + 128 * ai + 64 * wr + 16 * m + fr) * DM + u.pn * 256 + 32 * wc + 4 * fq;
; #pragma unroll
;                 for (int bj = 0; bj < 2; ++bj)
; #pragma unroll
;                     for (int n = 0; n < 2; ++n) acc[ai][bj][m][n] = __builtin_nontemporal_load((const f32x4*)(x + off + bj * HALF + n * 16)); }
; template <class Epi, class Sched, bool ALIGN_EPI = false, bool SP2 = false>
; __device__ __forceinline__ void gemm_phase(PG8_LAS unsigned char* lds, const Gemm g, const Sched& S, const Epi& E) {
;     ...
;             PG8_LDA(At, 1, 1); PG8_STAGE(PG8_SB(1, 0), b3, voffB); PG8_STAGE(PG8_SB(1, 1), b3 + hstep, voffB); PG8_STAGE(PG8_SA(1, 0), a3, voffA);
;             PG8_WAIT_V(8); PG8_WAIT_L(0); PG8_BAR; PG8_MMA(1, 0, At, B0); PG8_MMA(1, 1, At, B1); PG8_BAR; PG8_SCHED;
.Lxa_done_pl:
	s_add_i32 s92, s80, 4
	s_and_b32 s93, s92, 6
	s_lshl_b32 s93, s93, 15
	s_and_b32 s92, s92, 8
	s_lshl_b32 s92, s92, 16
	s_add_i32 s92, s92, s93
	s_cmp_eq_u32 s80, 12
	s_cselect_b32 s90, s86, s84
	s_cselect_b32 s91, s87, s85
	s_add_u32 s90, s90, s92
	s_addc_u32 s91, s91, 0
	v_lshl_add_u64 v[232:233], v[234:235], 0, s[90:91]
	global_load_dwordx4 v[216:219], v[232:233], off nt
	global_load_dwordx4 v[220:223], v[232:233], off offset:64 nt
	global_load_dwordx4 v[224:227], v[232:233], off offset:512 nt
	global_load_dwordx4 v[228:231], v[232:233], off offset:576 nt
	s_waitcnt vmcnt(12)
	s_waitcnt lgkmcnt(0)
	s_barrier
	s_setprio 1
	s_waitcnt lgkmcnt(0)
	v_mfma_f32_16x16x32_bf16 v[70:73], v[144:147], v[176:179], v[70:73]
	v_mfma_f32_16x16x32_bf16 v[66:69], v[152:155], v[176:179], v[66:69]
	v_mfma_f32_16x16x32_bf16 v[86:89], v[144:147], v[184:187], v[86:89]
	v_mfma_f32_16x16x32_bf16 v[82:85], v[152:155], v[184:187], v[82:85]
	v_mfma_f32_16x16x32_bf16 v[102:105], v[144:147], v[192:195], v[102:105]
	v_mfma_f32_16x16x32_bf16 v[98:101], v[152:155], v[192:195], v[98:101]
	v_mfma_f32_16x16x32_bf16 v[118:121], v[144:147], v[200:203], v[118:121]
	v_mfma_f32_16x16x32_bf16 v[114:117], v[152:155], v[200:203], v[114:117]
	v_mfma_f32_16x16x32_bf16 v[70:73], v[148:151], v[180:183], v[70:73]
	v_mfma_f32_16x16x32_bf16 v[66:69], v[156:159], v[180:183], v[66:69]
	v_mfma_f32_16x16x32_bf16 v[86:89], v[148:151], v[188:191], v[86:89]
	v_mfma_f32_16x16x32_bf16 v[82:85], v[156:159], v[188:191], v[82:85]
	v_mfma_f32_16x16x32_bf16 v[102:105], v[148:151], v[196:199], v[102:105]
	v_mfma_f32_16x16x32_bf16 v[98:101], v[156:159], v[196:199], v[98:101]
	v_mfma_f32_16x16x32_bf16 v[118:121], v[148:151], v[204:207], v[118:121]
	v_mfma_f32_16x16x32_bf16 v[114:117], v[156:159], v[204:207], v[114:117]
	v_mfma_f32_16x16x32_bf16 v[74:77], v[160:163], v[176:179], v[74:77]
	v_mfma_f32_16x16x32_bf16 v[78:81], v[168:171], v[176:179], v[78:81]
	v_mfma_f32_16x16x32_bf16 v[90:93], v[160:163], v[184:187], v[90:93]
	v_mfma_f32_16x16x32_bf16 v[94:97], v[168:171], v[184:187], v[94:97]
	v_mfma_f32_16x16x32_bf16 v[106:109], v[160:163], v[192:195], v[106:109]
	v_mfma_f32_16x16x32_bf16 v[110:113], v[168:171], v[192:195], v[110:113]
	v_mfma_f32_16x16x32_bf16 v[122:125], v[160:163], v[200:203], v[122:125]
	v_mfma_f32_16x16x32_bf16 v[126:129], v[168:171], v[200:203], v[126:129]
	v_mfma_f32_16x16x32_bf16 v[74:77], v[164:167], v[180:183], v[74:77]
	v_mfma_f32_16x16x32_bf16 v[78:81], v[172:175], v[180:183], v[78:81]
	v_mfma_f32_16x16x32_bf16 v[90:93], v[164:167], v[188:191], v[90:93]
	v_mfma_f32_16x16x32_bf16 v[94:97], v[172:175], v[188:191], v[94:97]
	v_mfma_f32_16x16x32_bf16 v[106:109], v[164:167], v[196:199], v[106:109]
	v_mfma_f32_16x16x32_bf16 v[110:113], v[172:175], v[196:199], v[110:113]
	v_mfma_f32_16x16x32_bf16 v[122:125], v[164:167], v[204:207], v[122:125]
	v_mfma_f32_16x16x32_bf16 v[126:129], v[172:175], v[204:207], v[126:129]
	s_setprio 0
	s_barrier
	s_add_i32 s80, s80, 2
	s_add_u32 s48, s48, 0x100
	s_addc_u32 s49, s49, 0
	s_add_u32 s78, s78, 0x100
	s_addc_u32 s79, s79, 0
	s_cmp_gt_u32 s80, 13
.LBB0_722:
	v_add_u32_e32 v140, s74, v138
	ds_read_b128 v[144:147], v140
	ds_read_b128 v[148:151], v140 offset:1024
	ds_read_b128 v[152:155], v140 offset:2048
	ds_read_b128 v[156:159], v140 offset:3072
	v_add_u32_e32 v140, s75, v138
	ds_read_b128 v[160:163], v140
	ds_read_b128 v[164:167], v140 offset:1024
	ds_read_b128 v[168:171], v140 offset:2048
	ds_read_b128 v[172:175], v140 offset:3072
	s_add_u32 s2, s48, 0xfffc0080
	s_addc_u32 s46, s49, -1
	s_cmp_eq_u32 s80, 12
	s_cselect_b32 s53, s29, s46
	s_cselect_b32 s52, s31, s2
	s_cselect_b32 s47, s39, s79
	s_cselect_b32 s46, s77, s78
	v_lshl_add_u64 v[140:141], s[48:49], 0, v[0:1]
	s_add_i32 m0, s64, 0xc000
	ds_read_b128 v[176:179], v139
	ds_read_b128 v[180:183], v139 offset:1024
	ds_read_b128 v[184:187], v139 offset:2048
	ds_read_b128 v[188:191], v139 offset:3072
	ds_read_b128 v[192:195], v139 offset:4096
	ds_read_b128 v[196:199], v139 offset:5120
	ds_read_b128 v[200:203], v139 offset:6144
	ds_read_b128 v[204:207], v139 offset:7168
	global_load_lds_dwordx4 v[140:141], off
	v_lshl_add_u64 v[140:141], s[48:49], 0, v[134:135]
	s_add_i32 m0, s64, 0xe000
	s_nop 0
	global_load_lds_dwordx4 v[140:141], off
	s_waitcnt vmcnt(12)
	s_waitcnt lgkmcnt(0)
	s_barrier
	s_setprio 1
	s_waitcnt lgkmcnt(0)
	v_mfma_f32_16x16x32_bf16 v[2:5], v[144:147], v[176:179], v[2:5]
	v_mfma_f32_16x16x32_bf16 v[6:9], v[152:155], v[176:179], v[6:9]
	v_mfma_f32_16x16x32_bf16 v[22:25], v[144:147], v[184:187], v[22:25]
	v_mfma_f32_16x16x32_bf16 v[18:21], v[152:155], v[184:187], v[18:21]
	v_mfma_f32_16x16x32_bf16 v[38:41], v[144:147], v[192:195], v[38:41]
	v_mfma_f32_16x16x32_bf16 v[34:37], v[152:155], v[192:195], v[34:37]
	v_mfma_f32_16x16x32_bf16 v[54:57], v[144:147], v[200:203], v[54:57]
	v_mfma_f32_16x16x32_bf16 v[50:53], v[152:155], v[200:203], v[50:53]
	v_mfma_f32_16x16x32_bf16 v[2:5], v[148:151], v[180:183], v[2:5]
	v_mfma_f32_16x16x32_bf16 v[6:9], v[156:159], v[180:183], v[6:9]
	v_mfma_f32_16x16x32_bf16 v[22:25], v[148:151], v[188:191], v[22:25]
	v_mfma_f32_16x16x32_bf16 v[18:21], v[156:159], v[188:191], v[18:21]
	v_mfma_f32_16x16x32_bf16 v[38:41], v[148:151], v[196:199], v[38:41]
	v_mfma_f32_16x16x32_bf16 v[34:37], v[156:159], v[196:199], v[34:37]
	v_mfma_f32_16x16x32_bf16 v[54:57], v[148:151], v[204:207], v[54:57]
	v_mfma_f32_16x16x32_bf16 v[50:53], v[156:159], v[204:207], v[50:53]
	v_mfma_f32_16x16x32_bf16 v[10:13], v[160:163], v[176:179], v[10:13]
	v_mfma_f32_16x16x32_bf16 v[14:17], v[168:171], v[176:179], v[14:17]
	v_mfma_f32_16x16x32_bf16 v[26:29], v[160:163], v[184:187], v[26:29]
	v_mfma_f32_16x16x32_bf16 v[30:33], v[168:171], v[184:187], v[30:33]
	v_mfma_f32_16x16x32_bf16 v[42:45], v[160:163], v[192:195], v[42:45]
	v_mfma_f32_16x16x32_bf16 v[46:49], v[168:171], v[192:195], v[46:49]
	v_mfma_f32_16x16x32_bf16 v[58:61], v[160:163], v[200:203], v[58:61]
	v_mfma_f32_16x16x32_bf16 v[62:65], v[168:171], v[200:203], v[62:65]
	v_mfma_f32_16x16x32_bf16 v[10:13], v[164:167], v[180:183], v[10:13]
	v_mfma_f32_16x16x32_bf16 v[14:17], v[172:175], v[180:183], v[14:17]
	v_mfma_f32_16x16x32_bf16 v[26:29], v[164:167], v[188:191], v[26:29]
	v_mfma_f32_16x16x32_bf16 v[30:33], v[172:175], v[188:191], v[30:33]
	v_mfma_f32_16x16x32_bf16 v[42:45], v[164:167], v[196:199], v[42:45]
	v_mfma_f32_16x16x32_bf16 v[46:49], v[172:175], v[196:199], v[46:49]
	v_mfma_f32_16x16x32_bf16 v[58:61], v[164:167], v[204:207], v[58:61]
	v_mfma_f32_16x16x32_bf16 v[62:65], v[172:175], v[204:207], v[62:65]
	s_setprio 0
	s_barrier
; #define PG8_STAGE(bufoff, gbase, voff) do { _Pragma("unroll") for (int _i = 0; _i < 2; ++_i) \
;         __builtin_amdgcn_global_load_lds((const unsigned*)((const char*)(gbase) + (voff)[_i]), (PG8_LAS unsigned*)(lds + (bufoff) + ldsw + _i * 8192), 16, 0, 0); } while (0)
; #define PG8_LDA(dst, b, h) do { _Pragma("unroll") for (int m = 0; m < 4; ++m) _Pragma("unroll") for (int k = 0; k < 2; ++k) dst[m][k] = *(const PG8_LAS bf16x8*)(lds + PG8_SA(b, h) + aoff + m * 2048 + k * 1024); } while (0)
; #define PG8_LDB(dst, b, h) do { _Pragma("unroll") for (int n = 0; n < 2; ++n) _Pragma("unroll") for (int k = 0; k < 2; ++k) dst[n][k] = *(const PG8_LAS bf16x8*)(lds + PG8_SB(b, h) + boff + n * 2048 + k * 1024); } while (0)
; #define PG8_MMA(ai, bj, At, Bt) do { __builtin_amdgcn_s_setprio(1); _Pragma("unroll") for (int m = 0; m < 4; ++m) _Pragma("unroll") for (int n = 0; n < 2; ++n) _Pragma("unroll") for (int k = 0; k < 2; ++k) \
;         acc[ai][bj][m][n] = __builtin_amdgcn_mfma_f32_16x16x32_bf16(Bt[n][k], At[m][k], acc[ai][bj][m][n], 0, 0, 0); __builtin_amdgcn_s_setprio(0); } while (0)
; #define PG8_WAIT_V(n) asm volatile("s_waitcnt vmcnt(" #n ")" ::: "memory")
; #define PG8_WAIT_L(n) asm volatile("s_waitcnt lgkmcnt(" #n ")" ::: "memory")
; #define PG8_BAR __builtin_amdgcn_s_barrier()
; #define PG8_SCHED __builtin_amdgcn_sched_barrier(0)
; template <class Epi, class Sched, bool ALIGN_EPI = false, bool SP2 = false>
; __device__ __forceinline__ void gemm_phase(PG8_LAS unsigned char* lds, const Gemm g, const Sched& S, const Epi& E) {
;     ...
;             PG8_LDA(At, 0, 1); PG8_STAGE(PG8_SB(0, 0), b2, voffB); PG8_STAGE(PG8_SB(0, 1), b2 + hstep, voffB); PG8_STAGE(PG8_SA(0, 0), a2, voffA);
;             PG8_WAIT_V(8); PG8_WAIT_L(0); PG8_BAR; PG8_MMA(1, 0, At, B0); PG8_MMA(1, 1, At, B1); PG8_BAR; PG8_SCHED;
;             PG8_LDB(B0, 1, 0); PG8_LDB(B1, 1, 1); PG8_SCHED; PG8_LDA(At, 1, 0); PG8_STAGE(PG8_SA(0, 1), a2 + hstep, voffA);
;             PG8_WAIT_V(8); PG8_WAIT_L(0); PG8_BAR; PG8_MMA(0, 0, At, B0); PG8_MMA(0, 1, At, B1); PG8_BAR; PG8_SCHED;
	s_add_i32 s2, s74, s57
	v_lshl_add_u64 v[140:141], s[46:47], 0, v[130:131]
	s_mov_b32 m0, s2
	ds_read_b128 v[176:179], v139 offset:16384
	ds_read_b128 v[180:183], v139 offset:17408
	ds_read_b128 v[184:187], v139 offset:18432
	ds_read_b128 v[188:191], v139 offset:19456
	ds_read_b128 v[192:195], v139 offset:20480
	ds_read_b128 v[196:199], v139 offset:21504
	ds_read_b128 v[200:203], v139 offset:22528
	ds_read_b128 v[204:207], v139 offset:23552
	global_load_lds_dwordx4 v[140:141], off
	s_add_i32 m0, s2, 0x2000
	s_add_u32 s82, s46, 0x40000
	v_lshl_add_u64 v[208:209], s[46:47], 0, v[132:133]
	s_addc_u32 s83, s47, 0
	s_add_i32 s2, s75, s57
	global_load_lds_dwordx4 v[208:209], off
	v_lshl_add_u64 v[210:211], s[82:83], 0, v[130:131]
	s_mov_b32 m0, s2
	v_lshl_add_u64 v[212:213], s[52:53], 0, v[132:133]
	global_load_lds_dwordx4 v[210:211], off
	v_lshl_add_u64 v[210:211], s[82:83], 0, v[132:133]
	s_add_i32 m0, s2, 0x2000
	s_nop 0
	global_load_lds_dwordx4 v[210:211], off
	v_lshl_add_u64 v[210:211], s[52:53], 0, v[130:131]
	s_mov_b32 m0, s64
	s_nop 0
	global_load_lds_dwordx4 v[210:211], off
	s_mov_b32 m0, s65
	s_nop 0
	global_load_lds_dwordx4 v[212:213], off
	s_waitcnt vmcnt(12)
	s_waitcnt lgkmcnt(0)
	s_barrier
	s_setprio 1
	s_waitcnt lgkmcnt(0)
	v_mfma_f32_16x16x32_bf16 v[70:73], v[144:147], v[176:179], v[70:73]
	v_mfma_f32_16x16x32_bf16 v[66:69], v[152:155], v[176:179], v[66:69]
	v_mfma_f32_16x16x32_bf16 v[86:89], v[144:147], v[184:187], v[86:89]
	v_mfma_f32_16x16x32_bf16 v[82:85], v[152:155], v[184:187], v[82:85]
	v_mfma_f32_16x16x32_bf16 v[102:105], v[144:147], v[192:195], v[102:105]
	v_mfma_f32_16x16x32_bf16 v[98:101], v[152:155], v[192:195], v[98:101]
	v_mfma_f32_16x16x32_bf16 v[118:121], v[144:147], v[200:203], v[118:121]
	v_mfma_f32_16x16x32_bf16 v[114:117], v[152:155], v[200:203], v[114:117]
	v_mfma_f32_16x16x32_bf16 v[70:73], v[148:151], v[180:183], v[70:73]
	v_mfma_f32_16x16x32_bf16 v[66:69], v[156:159], v[180:183], v[66:69]
	v_mfma_f32_16x16x32_bf16 v[86:89], v[148:151], v[188:191], v[86:89]
	v_mfma_f32_16x16x32_bf16 v[82:85], v[156:159], v[188:191], v[82:85]
	v_mfma_f32_16x16x32_bf16 v[102:105], v[148:151], v[196:199], v[102:105]
	v_mfma_f32_16x16x32_bf16 v[98:101], v[156:159], v[196:199], v[98:101]
	v_mfma_f32_16x16x32_bf16 v[118:121], v[148:151], v[204:207], v[118:121]
	v_mfma_f32_16x16x32_bf16 v[114:117], v[156:159], v[204:207], v[114:117]
	v_mfma_f32_16x16x32_bf16 v[74:77], v[160:163], v[176:179], v[74:77]
	v_mfma_f32_16x16x32_bf16 v[78:81], v[168:171], v[176:179], v[78:81]
	v_mfma_f32_16x16x32_bf16 v[90:93], v[160:163], v[184:187], v[90:93]
	v_mfma_f32_16x16x32_bf16 v[94:97], v[168:171], v[184:187], v[94:97]
	v_mfma_f32_16x16x32_bf16 v[106:109], v[160:163], v[192:195], v[106:109]
	v_mfma_f32_16x16x32_bf16 v[110:113], v[168:171], v[192:195], v[110:113]
	v_mfma_f32_16x16x32_bf16 v[122:125], v[160:163], v[200:203], v[122:125]
	v_mfma_f32_16x16x32_bf16 v[126:129], v[168:171], v[200:203], v[126:129]
	v_mfma_f32_16x16x32_bf16 v[74:77], v[164:167], v[180:183], v[74:77]
	v_mfma_f32_16x16x32_bf16 v[78:81], v[172:175], v[180:183], v[78:81]
	v_mfma_f32_16x16x32_bf16 v[90:93], v[164:167], v[188:191], v[90:93]
	v_mfma_f32_16x16x32_bf16 v[94:97], v[172:175], v[188:191], v[94:97]
	v_mfma_f32_16x16x32_bf16 v[106:109], v[164:167], v[196:199], v[106:109]
	v_mfma_f32_16x16x32_bf16 v[110:113], v[172:175], v[196:199], v[110:113]
	v_mfma_f32_16x16x32_bf16 v[122:125], v[164:167], v[204:207], v[122:125]
	v_mfma_f32_16x16x32_bf16 v[126:129], v[172:175], v[204:207], v[126:129]
	s_setprio 0
	s_barrier
	s_add_i32 s2, 0, 0x18000
	s_add_i32 s81, 0, 0x1c000
	v_add_u32_e32 v156, s2, v138
	v_add_u32_e32 v172, s81, v138
	ds_read_b128 v[144:147], v156
	ds_read_b128 v[148:151], v156 offset:1024
	ds_read_b128 v[152:155], v156 offset:2048
	ds_read_b128 v[156:159], v156 offset:3072
	ds_read_b128 v[160:163], v172
	ds_read_b128 v[164:167], v172 offset:1024
	ds_read_b128 v[168:171], v172 offset:2048
	ds_read_b128 v[172:175], v172 offset:3072
	s_add_u32 s52, s52, 0x40000
	s_addc_u32 s53, s53, 0
	s_mov_b32 m0, s66
	v_lshl_add_u64 v[214:215], s[52:53], 0, v[130:131]
	ds_read_b128 v[176:179], v139 offset:32768
	ds_read_b128 v[180:183], v139 offset:33792
	ds_read_b128 v[184:187], v139 offset:34816
	ds_read_b128 v[188:191], v139 offset:35840
	ds_read_b128 v[192:195], v139 offset:36864
	ds_read_b128 v[196:199], v139 offset:37888
	ds_read_b128 v[200:203], v139 offset:38912
	ds_read_b128 v[204:207], v139 offset:39936
	global_load_lds_dwordx4 v[214:215], off
	v_lshl_add_u64 v[214:215], s[52:53], 0, v[132:133]
	s_mov_b32 m0, s67
	s_nop 0
	global_load_lds_dwordx4 v[214:215], off
	s_waitcnt vmcnt(8)
	s_waitcnt lgkmcnt(0)
	s_barrier
; #define PG8_STAGE(bufoff, gbase, voff) do { _Pragma("unroll") for (int _i = 0; _i < 2; ++_i) \
;         __builtin_amdgcn_global_load_lds((const unsigned*)((const char*)(gbase) + (voff)[_i]), (PG8_LAS unsigned*)(lds + (bufoff) + ldsw + _i * 8192), 16, 0, 0); } while (0)
; #define PG8_LDA(dst, b, h) do { _Pragma("unroll") for (int m = 0; m < 4; ++m) _Pragma("unroll") for (int k = 0; k < 2; ++k) dst[m][k] = *(const PG8_LAS bf16x8*)(lds + PG8_SA(b, h) + aoff + m * 2048 + k * 1024); } while (0)
; #define PG8_MMA(ai, bj, At, Bt) do { __builtin_amdgcn_s_setprio(1); _Pragma("unroll") for (int m = 0; m < 4; ++m) _Pragma("unroll") for (int n = 0; n < 2; ++n) _Pragma("unroll") for (int k = 0; k < 2; ++k) \
;         acc[ai][bj][m][n] = __builtin_amdgcn_mfma_f32_16x16x32_bf16(Bt[n][k], At[m][k], acc[ai][bj][m][n], 0, 0, 0); __builtin_amdgcn_s_setprio(0); } while (0)
; #define PG8_WAIT_V(n) asm volatile("s_waitcnt vmcnt(" #n ")" ::: "memory")
; #define PG8_WAIT_L(n) asm volatile("s_waitcnt lgkmcnt(" #n ")" ::: "memory")
; #define PG8_BAR __builtin_amdgcn_s_barrier()
; #define PG8_SCHED __builtin_amdgcn_sched_barrier(0)
;     __device__ __forceinline__ void init(f32x4 (&acc)[2][2][4][2], const Unit& u, int wr, int wc, int fr, int fq) const {
;     ...
; #pragma unroll
;         for (int ai = 0; ai < 2; ++ai)
; #pragma unroll
;             for (int m = 0; m < 4; ++m) { const size_t off = ((size_t)u.pm * 256 + 128 * ai + 64 * wr + 16 * m + fr) * DM + u.pn * 256 + 32 * wc + 4 * fq;
; #pragma unroll
;                 for (int bj = 0; bj < 2; ++bj)
; #pragma unroll
;                     for (int n = 0; n < 2; ++n) acc[ai][bj][m][n] = __builtin_nontemporal_load((const f32x4*)(x + off + bj * HALF + n * 16)); }
; template <class Epi, class Sched, bool ALIGN_EPI = false, bool SP2 = false>
; __device__ __forceinline__ void gemm_phase(PG8_LAS unsigned char* lds, const Gemm g, const Sched& S, const Epi& E) {
;     ...
;             PG8_WAIT_V(8); PG8_WAIT_L(0); PG8_BAR; PG8_MMA(0, 0, At, B0); PG8_MMA(0, 1, At, B1); PG8_BAR; PG8_SCHED;
;             PG8_LDA(At, 1, 1); PG8_STAGE(PG8_SB(1, 0), b3, voffB); PG8_STAGE(PG8_SB(1, 1), b3 + hstep, voffB); PG8_STAGE(PG8_SA(1, 0), a3, voffA);
;             PG8_WAIT_V(8); PG8_WAIT_L(0); PG8_BAR; PG8_MMA(1, 0, At, B0); PG8_MMA(1, 1, At, B1); PG8_BAR; PG8_SCHED;
	s_setprio 1
	s_waitcnt lgkmcnt(0)
	v_mfma_f32_16x16x32_bf16 v[2:5], v[144:147], v[176:179], v[2:5]
	v_mfma_f32_16x16x32_bf16 v[6:9], v[152:155], v[176:179], v[6:9]
	v_mfma_f32_16x16x32_bf16 v[22:25], v[144:147], v[184:187], v[22:25]
	v_mfma_f32_16x16x32_bf16 v[18:21], v[152:155], v[184:187], v[18:21]
	v_mfma_f32_16x16x32_bf16 v[38:41], v[144:147], v[192:195], v[38:41]
	v_mfma_f32_16x16x32_bf16 v[34:37], v[152:155], v[192:195], v[34:37]
	v_mfma_f32_16x16x32_bf16 v[54:57], v[144:147], v[200:203], v[54:57]
	v_mfma_f32_16x16x32_bf16 v[50:53], v[152:155], v[200:203], v[50:53]
	v_mfma_f32_16x16x32_bf16 v[2:5], v[148:151], v[180:183], v[2:5]
	v_mfma_f32_16x16x32_bf16 v[6:9], v[156:159], v[180:183], v[6:9]
	v_mfma_f32_16x16x32_bf16 v[22:25], v[148:151], v[188:191], v[22:25]
	v_mfma_f32_16x16x32_bf16 v[18:21], v[156:159], v[188:191], v[18:21]
	v_mfma_f32_16x16x32_bf16 v[38:41], v[148:151], v[196:199], v[38:41]
	v_mfma_f32_16x16x32_bf16 v[34:37], v[156:159], v[196:199], v[34:37]
	v_mfma_f32_16x16x32_bf16 v[54:57], v[148:151], v[204:207], v[54:57]
	v_mfma_f32_16x16x32_bf16 v[50:53], v[156:159], v[204:207], v[50:53]
	v_mfma_f32_16x16x32_bf16 v[10:13], v[160:163], v[176:179], v[10:13]
	v_mfma_f32_16x16x32_bf16 v[14:17], v[168:171], v[176:179], v[14:17]
	v_mfma_f32_16x16x32_bf16 v[26:29], v[160:163], v[184:187], v[26:29]
	v_mfma_f32_16x16x32_bf16 v[30:33], v[168:171], v[184:187], v[30:33]
	v_mfma_f32_16x16x32_bf16 v[42:45], v[160:163], v[192:195], v[42:45]
	v_mfma_f32_16x16x32_bf16 v[46:49], v[168:171], v[192:195], v[46:49]
	v_mfma_f32_16x16x32_bf16 v[58:61], v[160:163], v[200:203], v[58:61]
	v_mfma_f32_16x16x32_bf16 v[62:65], v[168:171], v[200:203], v[62:65]
	v_mfma_f32_16x16x32_bf16 v[10:13], v[164:167], v[180:183], v[10:13]
	v_mfma_f32_16x16x32_bf16 v[14:17], v[172:175], v[180:183], v[14:17]
	v_mfma_f32_16x16x32_bf16 v[26:29], v[164:167], v[188:191], v[26:29]
	v_mfma_f32_16x16x32_bf16 v[30:33], v[172:175], v[188:191], v[30:33]
	v_mfma_f32_16x16x32_bf16 v[42:45], v[164:167], v[196:199], v[42:45]
	v_mfma_f32_16x16x32_bf16 v[46:49], v[172:175], v[196:199], v[46:49]
	v_mfma_f32_16x16x32_bf16 v[58:61], v[164:167], v[204:207], v[58:61]
	v_mfma_f32_16x16x32_bf16 v[62:65], v[172:175], v[204:207], v[62:65]
	s_setprio 0
	s_barrier
	s_add_i32 s2, s2, s57
	v_lshl_add_u64 v[140:141], v[140:141], 0, s[26:27]
	s_mov_b32 m0, s2
	ds_read_b128 v[176:179], v139 offset:49152
	ds_read_b128 v[180:183], v139 offset:50176
	ds_read_b128 v[184:187], v139 offset:51200
	ds_read_b128 v[188:191], v139 offset:52224
	ds_read_b128 v[192:195], v139 offset:53248
	ds_read_b128 v[196:199], v139 offset:54272
	ds_read_b128 v[200:203], v139 offset:55296
	ds_read_b128 v[204:207], v139 offset:56320
	global_load_lds_dwordx4 v[140:141], off
	s_add_i32 m0, s2, 0x2000
	s_add_u32 s46, s46, 0x40080
	v_lshl_add_u64 v[140:141], v[208:209], 0, s[26:27]
	s_addc_u32 s47, s47, 0
	s_add_i32 s2, s81, s57
	global_load_lds_dwordx4 v[140:141], off
	v_lshl_add_u64 v[140:141], s[46:47], 0, v[130:131]
	s_mov_b32 m0, s2
	s_nop 0
	global_load_lds_dwordx4 v[140:141], off
	v_lshl_add_u64 v[140:141], s[46:47], 0, v[132:133]
	s_add_i32 m0, s2, 0x2000
	s_nop 0
	global_load_lds_dwordx4 v[140:141], off
	v_lshl_add_u64 v[140:141], v[210:211], 0, s[26:27]
	s_mov_b32 m0, s68
	s_nop 0
	global_load_lds_dwordx4 v[140:141], off
	v_lshl_add_u64 v[140:141], v[212:213], 0, s[26:27]
	s_mov_b32 m0, s69
	s_nop 0
	global_load_lds_dwordx4 v[140:141], off
	s_cmp_lt_i32 s80, 6
	s_cbranch_scc0 .Lxa_hi
	s_cmp_lt_i32 s80, 2
	s_cbranch_scc0 .Lxa_23
	s_cmp_lt_i32 s80, 0
	s_cbranch_scc0 .Lxa_1
	v_add_f32_e32 v2, v2, v216
	v_add_f32_e32 v3, v3, v217
	v_add_f32_e32 v4, v4, v218
	v_add_f32_e32 v5, v5, v219
	v_add_f32_e32 v6, v6, v220
	v_add_f32_e32 v7, v7, v221
	v_add_f32_e32 v8, v8, v222
	v_add_f32_e32 v9, v9, v223
	v_add_f32_e32 v10, v10, v224
	v_add_f32_e32 v11, v11, v225
	v_add_f32_e32 v12, v12, v226
	v_add_f32_e32 v13, v13, v227
	v_add_f32_e32 v14, v14, v228
	v_add_f32_e32 v15, v15, v229
	v_add_f32_e32 v16, v16, v230
	v_add_f32_e32 v17, v17, v231
	s_branch .Lxa_done

;     __device__ __forceinline__ void operator()(f32x4 (&acc)[2][2][4][2], const Unit& u, int wr, int wc, int fr, int fq) const {
;         asm volatile("" : "+v"(fr)); asm volatile("" : "+v"(fq));
; #pragma unroll
;         for (int ai = 0; ai < 2; ++ai)
; #pragma unroll
;             for (int m = 0; m < 4; ++m) { const size_t off = ((size_t)u.pm * 256 + 128 * ai + 64 * wr + 16 * m + fr) * DM + u.pn * 256 + 32 * wc + 4 * fq;
; #pragma unroll
;                 for (int bj = 0; bj < 2; ++bj)
; #pragma unroll
;                     for (int n = 0; n < 2; ++n) *(f32x4*)(out + off + bj * HALF + n * 16) = acc[ai][bj][m][n]; }
;     }
; template <class Epi, class Sched, bool ALIGN_EPI = false, bool SP2 = false>
; __device__ __forceinline__ void gemm_phase(PG8_LAS unsigned char* lds, const Gemm g, const Sched& S, const Epi& E) {
;     ...
;         if (!has_next) break;
; #pragma unroll
;         for (int a = 0; a < 2; ++a)
; #pragma unroll
;             for (int b = 0; b < 2; ++b)
; #pragma unroll
;                 for (int m = 0; m < 4; ++m)
; #pragma unroll
;                     for (int n = 0; n < 2; ++n) acc[a][b][m][n] = (f32x4){0.f, 0.f, 0.f, 0.f};
.LBB0_725:
	s_ashr_i32 s31, s30, 31
	s_lshl_b64 s[30:31], s[30:31], 8
	v_mov_b32_e32 v140, v142
	s_add_u32 s30, s30, s4
	s_addc_u32 s31, s31, 0
	v_ashrrev_i32_e32 v141, 31, v140
	v_lshl_add_u64 v[140:141], s[30:31], 0, v[140:141]
	v_mov_b32_e32 v144, v143
	s_lshl_b32 s28, s28, 8
	v_lshlrev_b64 v[140:141], 12, v[140:141]
	s_ashr_i32 s29, s28, 31
	v_lshl_add_u64 v[140:141], s[50:51], 0, v[140:141]
	v_lshlrev_b32_e32 v144, 2, v144
	v_lshl_add_u64 v[140:141], s[28:29], 2, v[140:141]
	v_ashrrev_i32_e32 v145, 31, v144
	v_lshl_add_u64 v[140:141], v[140:141], 0, s[6:7]
	v_lshl_add_u64 v[140:141], v[144:145], 2, v[140:141]
	global_store_dwordx4 v[140:141], v[2:5], off
	global_store_dwordx4 v[140:141], v[6:9], off offset:64
	global_store_dwordx4 v[140:141], v[10:13], off offset:512
	global_store_dwordx4 v[140:141], v[14:17], off offset:576
	v_add_co_u32_e32 v4, vcc, s58, v140
	v_lshl_add_u64 v[2:3], v[140:141], 0, s[8:9]
	s_nop 0
	v_addc_co_u32_e32 v5, vcc, 0, v141, vcc
	global_store_dwordx4 v[4:5], v[22:25], off
	global_store_dwordx4 v[2:3], v[18:21], off offset:64
	global_store_dwordx4 v[2:3], v[26:29], off offset:512
	global_store_dwordx4 v[2:3], v[30:33], off offset:576
	v_add_co_u32_e32 v4, vcc, s59, v140
	v_lshl_add_u64 v[2:3], v[140:141], 0, s[10:11]
	s_nop 0
	v_addc_co_u32_e32 v5, vcc, 0, v141, vcc
	global_store_dwordx4 v[4:5], v[38:41], off
	global_store_dwordx4 v[2:3], v[34:37], off offset:64
	global_store_dwordx4 v[2:3], v[42:45], off offset:512
	global_store_dwordx4 v[2:3], v[46:49], off offset:576
	v_add_co_u32_e32 v4, vcc, s60, v140
	v_lshl_add_u64 v[2:3], v[140:141], 0, s[12:13]
	s_nop 0
	v_addc_co_u32_e32 v5, vcc, 0, v141, vcc
	global_store_dwordx4 v[4:5], v[54:57], off
	global_store_dwordx4 v[2:3], v[50:53], off offset:64
	global_store_dwordx4 v[2:3], v[58:61], off offset:512
	global_store_dwordx4 v[2:3], v[62:65], off offset:576
	v_add_co_u32_e32 v4, vcc, s61, v140
	v_lshl_add_u64 v[2:3], v[140:141], 0, s[14:15]
	s_nop 0
	v_addc_co_u32_e32 v5, vcc, 0, v141, vcc
	global_store_dwordx4 v[4:5], v[70:73], off
	global_store_dwordx4 v[2:3], v[66:69], off offset:64
	global_store_dwordx4 v[2:3], v[74:77], off offset:512
	global_store_dwordx4 v[2:3], v[78:81], off offset:576
	v_add_co_u32_e32 v4, vcc, s62, v140
	v_lshl_add_u64 v[2:3], v[140:141], 0, s[18:19]
	s_nop 0
	v_addc_co_u32_e32 v5, vcc, 0, v141, vcc
	global_store_dwordx4 v[4:5], v[86:89], off
	global_store_dwordx4 v[2:3], v[82:85], off offset:64
	global_store_dwordx4 v[2:3], v[90:93], off offset:512
	global_store_dwordx4 v[2:3], v[94:97], off offset:576
	v_add_co_u32_e32 v4, vcc, s63, v140
	v_lshl_add_u64 v[2:3], v[140:141], 0, s[20:21]
	s_nop 0
	v_addc_co_u32_e32 v5, vcc, 0, v141, vcc
	global_store_dwordx4 v[4:5], v[102:105], off
	global_store_dwordx4 v[2:3], v[98:101], off offset:64
	global_store_dwordx4 v[2:3], v[106:109], off offset:512
	global_store_dwordx4 v[2:3], v[110:113], off offset:576
	v_add_co_u32_e32 v4, vcc, 0xb0000, v140
	v_lshl_add_u64 v[2:3], v[140:141], 0, s[22:23]
	s_nop 0
	v_addc_co_u32_e32 v5, vcc, 0, v141, vcc
	s_andn2_b64 vcc, exec, s[44:45]
	s_mov_b64 s[28:29], -1
	global_store_dwordx4 v[4:5], v[118:121], off
	global_store_dwordx4 v[2:3], v[114:117], off offset:64
	global_store_dwordx4 v[2:3], v[122:125], off offset:512
	global_store_dwordx4 v[2:3], v[126:129], off offset:576
	s_cbranch_vccnz .LBB0_709
	s_andn2_b64 vcc, exec, s[24:25]
	s_cbranch_vccnz .LBB0_708
	s_barrier
	s_branch .LBB0_708
